# scan recurrence reformulated: next dot computed as alpha + ar*beta (alpha=A.K', beta=B.K' off-chain) to shorten the dependent chain; f32 reassociation only
# speedup vs baseline: 1.0050x; 1.0050x over previous
; __device__ void scan_block(const Params& P, int sb, unsigned char* lds) {
;     ...
;     __builtin_amdgcn_s_setprio(2);
;     __syncthreads();
;     for (int c = 0; c < NCH; ++c) {
;       const float* b = buf + (c & 1) * SC_STAGE;
;       const float* q = b + ks * 4;
;       const float* qv = b + 320 + myrow;
;       float* yo = Y + (size_t)(c * SC_CH + ks) * 1024 + hb + rg * 16 + myrow;
;       f32x4 w4 = *(const f32x4*)(q), k4 = *(const f32x4*)(q + 64), b4 = *(const f32x4*)(q + 128), kh4 = *(const f32x4*)(q + 192), r4 = *(const f32x4*)(q + 256);
;       float v = qv[0];
;       float yk = 0.f, ypart = 0.f;
; #pragma unroll
;       for (int s = 0; s < SC_CH; ++s) {
;         f32x4 w4n, k4n, b4n, kh4n, r4n; float vn;
;         if (s + 1 < SC_CH) {
;           const float* qn = q + (s + 1) * SC_STEP;
;           w4n = *(const f32x4*)(qn); k4n = *(const f32x4*)(qn + 64); b4n = *(const f32x4*)(qn + 128); kh4n = *(const f32x4*)(qn + 192); r4n = *(const f32x4*)(qn + 256);
;           vn = qv[(s + 1) * SC_STEP];
;         }
;         __builtin_amdgcn_sched_barrier(0);
;         if (s > 0) {
;           const float y = dpp_allreduce16(ypart);
;           yk = (ks == ((s - 1) & 15)) ? y : yk;
;           if (((s - 1) & 15) == 15) yo[(size_t)(s - 16) * 1024] = yk;
;         }
;         const f32x2 pp = (f32x2){S[0], S[1]} * (f32x2){k4[0], k4[1]} + (f32x2){S[2], S[3]} * (f32x2){k4[2], k4[3]};
;         const f32x4 A = S * w4 + v * kh4;
;         const float ar = dpp_allreduce16(pp.x + pp.y);
;         S = A + ar * b4;
;         const f32x2 yy = (f32x2){S[0], S[1]} * (f32x2){r4[0], r4[1]} + (f32x2){S[2], S[3]} * (f32x2){r4[2], r4[3]};
;         ypart = yy.x + yy.y;
;         if (s + 1 < SC_CH) { w4 = w4n; k4 = k4n; b4 = b4n; kh4 = kh4n; r4 = r4n; v = vn; }
;       }
.LBB0_50:
	s_andn2_b64 vcc, exec, s[8:9]
	v_readlane_b32 s3, v252, 9
	s_cbranch_vccnz .LBB0_150
	v_readlane_b32 s2, v252, 0
	v_mov_b32_e32 v149, v169
	s_movk_i32 s0, 0x100
	s_nop 0
	v_cmp_gt_i32_e32 vcc, s0, v149
	s_lshl_b32 s0, s2, 4
	s_and_b32 s12, s0, 0xffffffc0
	s_barrier
	s_and_saveexec_b64 s[0:1], vcc
	s_xor_b64 s[82:83], exec, s[0:1]
	s_cbranch_execz .LBB0_55
	s_mov_b64 s[90:91], s[62:63]
	v_bfe_u32 v8, v149, 4, 4
	v_and_b32_e32 v0, 15, v149
	s_setprio 2
	s_ashr_i32 s13, s12, 31
	s_and_b32 s6, s2, 3
	s_lshl_b32 s8, s6, 6
	s_lshl_b64 s[6:7], s[12:13], 2
	s_add_u32 s6, s6, s8
	s_addc_u32 s7, s7, 0
	v_readlane_b32 s4, v251, 36
	v_readlane_b32 s5, v251, 37
	v_and_b32_e32 v2, 2, v0
	v_and_b32_e32 v3, 1, v0
	s_add_u32 s4, s4, s6
	s_addc_u32 s5, s5, s7
	v_cmp_ne_u32_e64 s[40:41], 0, v2
	v_cmp_ne_u32_e64 s[42:43], 0, v3
	v_lshl_add_u32 v9, v0, 4, 16
	v_lshl_add_u32 v10, v8, 2, 16
	v_bfrev_b32_e32 v2, v0
	v_lshrrev_b32_e32 v2, 16, v2
	v_lshl_add_u32 v2, v8, 2, v2
	v_add_u32_e32 v3, 0x10000, v2
	v_mov_b32_e32 v4, 0
	v_mov_b32_e32 v5, 0
	v_mov_b32_e32 v6, 0
	v_mov_b32_e32 v7, 0
	s_mov_b32 s3, 0
	s_waitcnt vmcnt(0)
	s_barrier
	v_mov_b32_e32 v118, 0
	v_mov_b32_e32 v119, 0
	v_mov_b32_e32 v112, 0
	v_mov_b32_e32 v54, 0
	v_mov_b32_e32 v55, 0
	v_mov_b32_e32 v56, 0
	v_mov_b32_e32 v57, 0
	v_mov_b32_e32 v108, 0
	v_mov_b32_e32 v109, 0
	v_mov_b32_e32 v110, 0
	v_mov_b32_e32 v111, 0
	ds_read_b128 v[60:63], v9 offset:1600
	ds_read_b128 v[68:71], v9 offset:2944
	ds_read_b128 v[76:79], v9 offset:4288
	ds_read_b128 v[16:19], v9 offset:0
	ds_read_b128 v[20:23], v9 offset:768
	ds_read_b32 v24, v10 offset:1280
	ds_read_b128 v[44:47], v9 offset:512
	ds_read_b128 v[64:67], v9 offset:1344
	ds_read_b128 v[28:31], v9 offset:2112
	ds_read_b32 v32, v10 offset:2624
	ds_read_b128 v[48:51], v9 offset:1856
	ds_read_b128 v[72:75], v9 offset:2688
	ds_read_b128 v[84:87], v9 offset:3456
	ds_read_b32 v92, v10 offset:3968
	ds_read_b128 v[104:107], v9 offset:3200
	ds_read_b128 v[36:39], v9 offset:1024
	ds_read_b128 v[40:43], v9 offset:2368
	s_waitcnt lgkmcnt(0)
.Lscan_top:
	s_waitcnt lgkmcnt(6)
	v_fma_f32 v52, v119, v112, v118
	v_pk_fma_f32 v[6:7], v[110:111], v[112:113], v[56:57] op_sel_hi:[1,0,1]
	v_pk_fma_f32 v[4:5], v[108:109], v[112:113], v[54:55] op_sel_hi:[1,0,1]
	v_add_f32_dpp v52, v52, v52 quad_perm:[1,0,3,2] row_mask:0xf bank_mask:0xf bound_ctrl:1
	v_pk_mul_f32 v[56:57], v[6:7], v[18:19]
	v_pk_mul_f32 v[54:55], v[4:5], v[16:17]
	v_add_f32_dpp v52, v52, v52 quad_perm:[2,3,0,1] row_mask:0xf bank_mask:0xf bound_ctrl:1
	v_pk_fma_f32 v[56:57], v[22:23], v[24:25], v[56:57] op_sel_hi:[1,0,1]
	v_pk_fma_f32 v[54:55], v[20:21], v[24:25], v[54:55] op_sel_hi:[1,0,1]
	v_add_f32_dpp v52, v52, v52 row_half_mirror row_mask:0xf bank_mask:0xf bound_ctrl:1
	s_nop 1
	v_add_f32_dpp v52, v52, v52 row_mirror row_mask:0xf bank_mask:0xf bound_ctrl:1
	v_pk_mul_f32 v[114:115], v[56:57], v[62:63]
	v_pk_mul_f32 v[116:117], v[46:47], v[62:63]
	v_pk_fma_f32 v[114:115], v[54:55], v[60:61], v[114:115]
	v_pk_fma_f32 v[116:117], v[44:45], v[60:61], v[116:117]
	v_add_f32_e32 v118, v114, v115
	v_add_f32_e32 v119, v116, v117
	ds_read_b128 v[12:15], v9 offset:5632
	ds_read_b128 v[80:83], v9 offset:4032
	ds_read_b128 v[88:91], v9 offset:4800
	ds_read_b32 v94, v10 offset:5312
	ds_read_b128 v[108:111], v9 offset:4544
	ds_read_b128 v[96:99], v9 offset:3712
	v_fma_f32 v112, v119, v52, v118
	v_pk_fma_f32 v[6:7], v[46:47], v[52:53], v[56:57] op_sel_hi:[1,0,1]
	v_pk_fma_f32 v[4:5], v[44:45], v[52:53], v[54:55] op_sel_hi:[1,0,1]
	v_add_f32_dpp v112, v112, v112 quad_perm:[1,0,3,2] row_mask:0xf bank_mask:0xf bound_ctrl:1
	v_pk_mul_f32 v[56:57], v[6:7], v[66:67]
	v_pk_mul_f32 v[54:55], v[4:5], v[64:65]
	v_add_f32_dpp v112, v112, v112 quad_perm:[2,3,0,1] row_mask:0xf bank_mask:0xf bound_ctrl:1
	v_pk_fma_f32 v[56:57], v[30:31], v[32:33], v[56:57] op_sel_hi:[1,0,1]
	v_pk_fma_f32 v[54:55], v[28:29], v[32:33], v[54:55] op_sel_hi:[1,0,1]
	v_add_f32_dpp v112, v112, v112 row_half_mirror row_mask:0xf bank_mask:0xf bound_ctrl:1
	v_pk_mul_f32 v[26:27], v[6:7], v[38:39]
	s_nop 0
	v_add_f32_dpp v112, v112, v112 row_mirror row_mask:0xf bank_mask:0xf bound_ctrl:1
	v_pk_mul_f32 v[114:115], v[56:57], v[70:71]
	v_pk_mul_f32 v[116:117], v[50:51], v[70:71]
	v_pk_fma_f32 v[114:115], v[54:55], v[68:69], v[114:115]
	v_pk_fma_f32 v[116:117], v[48:49], v[68:69], v[116:117]
	v_pk_fma_f32 v[26:27], v[4:5], v[36:37], v[26:27]
	v_add_f32_e32 v118, v114, v115
	v_add_f32_e32 v119, v116, v117
	ds_read_b128 v[60:63], v9 offset:6976
	ds_read_b128 v[16:19], v9 offset:5376
	ds_read_b128 v[20:23], v9 offset:6144
	ds_read_b32 v24, v10 offset:6656
	ds_read_b128 v[44:47], v9 offset:5888
	ds_read_b128 v[100:103], v9 offset:5056
	v_add_f32_e32 v25, v26, v27
	s_waitcnt lgkmcnt(6)
; __device__ void scan_block(const Params& P, int sb, unsigned char* lds) {
;     ...
;       for (int s = 0; s < SC_CH; ++s) {
;         f32x4 w4n, k4n, b4n, kh4n, r4n; float vn;
;         if (s + 1 < SC_CH) {
;           const float* qn = q + (s + 1) * SC_STEP;
;           w4n = *(const f32x4*)(qn); k4n = *(const f32x4*)(qn + 64); b4n = *(const f32x4*)(qn + 128); kh4n = *(const f32x4*)(qn + 192); r4n = *(const f32x4*)(qn + 256);
;           vn = qv[(s + 1) * SC_STEP];
;         }
;         __builtin_amdgcn_sched_barrier(0);
;         if (s > 0) {
;           const float y = dpp_allreduce16(ypart);
;           yk = (ks == ((s - 1) & 15)) ? y : yk;
;           if (((s - 1) & 15) == 15) yo[(size_t)(s - 16) * 1024] = yk;
;         }
;         const f32x2 pp = (f32x2){S[0], S[1]} * (f32x2){k4[0], k4[1]} + (f32x2){S[2], S[3]} * (f32x2){k4[2], k4[3]};
;         const f32x4 A = S * w4 + v * kh4;
;         const float ar = dpp_allreduce16(pp.x + pp.y);
;         S = A + ar * b4;
;         const f32x2 yy = (f32x2){S[0], S[1]} * (f32x2){r4[0], r4[1]} + (f32x2){S[2], S[3]} * (f32x2){r4[2], r4[3]};
;         ypart = yy.x + yy.y;
;         if (s + 1 < SC_CH) { w4 = w4n; k4 = k4n; b4 = b4n; kh4 = kh4n; r4 = r4n; v = vn; }
;       }
	v_fma_f32 v52, v119, v112, v118
	v_pk_fma_f32 v[6:7], v[50:51], v[112:113], v[56:57] op_sel_hi:[1,0,1]
	v_pk_fma_f32 v[4:5], v[48:49], v[112:113], v[54:55] op_sel_hi:[1,0,1]
	v_add_f32_dpp v52, v52, v52 quad_perm:[1,0,3,2] row_mask:0xf bank_mask:0xf bound_ctrl:1
	v_pk_mul_f32 v[56:57], v[6:7], v[74:75]
	v_pk_mul_f32 v[54:55], v[4:5], v[72:73]
	v_add_f32_dpp v52, v52, v52 quad_perm:[2,3,0,1] row_mask:0xf bank_mask:0xf bound_ctrl:1
	v_pk_fma_f32 v[56:57], v[86:87], v[92:93], v[56:57] op_sel_hi:[1,0,1]
	v_pk_fma_f32 v[54:55], v[84:85], v[92:93], v[54:55] op_sel_hi:[1,0,1]
	v_add_f32_dpp v52, v52, v52 row_half_mirror row_mask:0xf bank_mask:0xf bound_ctrl:1
	v_pk_mul_f32 v[26:27], v[6:7], v[42:43]
	v_add_f32_dpp v34, v25, v25 row_ror:8 row_mask:0xf bank_mask:0x3
	v_add_f32_dpp v52, v52, v52 row_mirror row_mask:0xf bank_mask:0xf bound_ctrl:1
	v_pk_mul_f32 v[114:115], v[56:57], v[78:79]
	v_pk_mul_f32 v[116:117], v[106:107], v[78:79]
	v_pk_fma_f32 v[114:115], v[54:55], v[76:77], v[114:115]
	v_pk_fma_f32 v[116:117], v[104:105], v[76:77], v[116:117]
	v_pk_fma_f32 v[26:27], v[4:5], v[40:41], v[26:27]
	v_add_f32_e32 v118, v114, v115
	v_add_f32_e32 v119, v116, v117
	ds_read_b128 v[68:71], v9 offset:8320
	ds_read_b128 v[64:67], v9 offset:6720
	ds_read_b128 v[28:31], v9 offset:7488
	ds_read_b32 v32, v10 offset:8000
	ds_read_b128 v[48:51], v9 offset:7232
	ds_read_b128 v[36:39], v9 offset:6400
	v_add_f32_e32 v25, v26, v27
	v_fma_f32 v112, v119, v52, v118
	v_pk_fma_f32 v[6:7], v[106:107], v[52:53], v[56:57] op_sel_hi:[1,0,1]
	v_pk_fma_f32 v[4:5], v[104:105], v[52:53], v[54:55] op_sel_hi:[1,0,1]
	v_add_f32_dpp v112, v112, v112 quad_perm:[1,0,3,2] row_mask:0xf bank_mask:0xf bound_ctrl:1
	v_pk_mul_f32 v[56:57], v[6:7], v[82:83]
	v_pk_mul_f32 v[54:55], v[4:5], v[80:81]
	v_add_f32_dpp v112, v112, v112 quad_perm:[2,3,0,1] row_mask:0xf bank_mask:0xf bound_ctrl:1
	v_pk_fma_f32 v[56:57], v[90:91], v[94:95], v[56:57] op_sel_hi:[1,0,1]
	v_pk_fma_f32 v[54:55], v[88:89], v[94:95], v[54:55] op_sel_hi:[1,0,1]
	v_add_f32_dpp v112, v112, v112 row_half_mirror row_mask:0xf bank_mask:0xf bound_ctrl:1
	v_pk_mul_f32 v[26:27], v[6:7], v[98:99]
	v_add_f32_dpp v34, v25, v25 row_ror:8 row_mask:0xf bank_mask:0xc
	v_add_f32_dpp v112, v112, v112 row_mirror row_mask:0xf bank_mask:0xf bound_ctrl:1
	v_pk_mul_f32 v[114:115], v[56:57], v[14:15]
	v_pk_mul_f32 v[116:117], v[110:111], v[14:15]
	v_pk_fma_f32 v[114:115], v[54:55], v[12:13], v[114:115]
	v_pk_fma_f32 v[116:117], v[108:109], v[12:13], v[116:117]
	v_pk_fma_f32 v[26:27], v[4:5], v[96:97], v[26:27]
	v_add_f32_e32 v118, v114, v115
	v_add_f32_e32 v119, v116, v117
	ds_read_b128 v[76:79], v9 offset:9664
	ds_read_b128 v[72:75], v9 offset:8064
	ds_read_b128 v[84:87], v9 offset:8832
	ds_read_b32 v92, v10 offset:9344
	ds_read_b128 v[104:107], v9 offset:8576
	ds_read_b128 v[40:43], v9 offset:7744
	v_add_f32_e32 v25, v26, v27
	v_add_f32_dpp v35, v34, v34 row_half_mirror row_mask:0xf bank_mask:0x5
	s_waitcnt lgkmcnt(6)
	v_fma_f32 v52, v119, v112, v118
	v_pk_fma_f32 v[6:7], v[110:111], v[112:113], v[56:57] op_sel_hi:[1,0,1]
	v_pk_fma_f32 v[4:5], v[108:109], v[112:113], v[54:55] op_sel_hi:[1,0,1]
	v_add_f32_dpp v52, v52, v52 quad_perm:[1,0,3,2] row_mask:0xf bank_mask:0xf bound_ctrl:1
	v_pk_mul_f32 v[56:57], v[6:7], v[18:19]
	v_pk_mul_f32 v[54:55], v[4:5], v[16:17]
	v_add_f32_dpp v52, v52, v52 quad_perm:[2,3,0,1] row_mask:0xf bank_mask:0xf bound_ctrl:1
	v_pk_fma_f32 v[56:57], v[22:23], v[24:25], v[56:57] op_sel_hi:[1,0,1]
	v_pk_fma_f32 v[54:55], v[20:21], v[24:25], v[54:55] op_sel_hi:[1,0,1]
	v_add_f32_dpp v52, v52, v52 row_half_mirror row_mask:0xf bank_mask:0xf bound_ctrl:1
	v_pk_mul_f32 v[26:27], v[6:7], v[102:103]
	v_add_f32_dpp v34, v25, v25 row_ror:8 row_mask:0xf bank_mask:0x3
	v_add_f32_dpp v52, v52, v52 row_mirror row_mask:0xf bank_mask:0xf bound_ctrl:1
	v_pk_mul_f32 v[114:115], v[56:57], v[62:63]
	v_pk_mul_f32 v[116:117], v[46:47], v[62:63]
	v_pk_fma_f32 v[114:115], v[54:55], v[60:61], v[114:115]
	v_pk_fma_f32 v[116:117], v[44:45], v[60:61], v[116:117]
	v_pk_fma_f32 v[26:27], v[4:5], v[100:101], v[26:27]
	v_add_f32_e32 v118, v114, v115
	v_add_f32_e32 v119, v116, v117
	ds_read_b128 v[12:15], v9 offset:11008
	ds_read_b128 v[80:83], v9 offset:9408
	ds_read_b128 v[88:91], v9 offset:10176
	ds_read_b32 v94, v10 offset:10688
	ds_read_b128 v[108:111], v9 offset:9920
	ds_read_b128 v[96:99], v9 offset:9088
	v_add_f32_e32 v25, v26, v27
	v_fma_f32 v112, v119, v52, v118
	v_pk_fma_f32 v[6:7], v[46:47], v[52:53], v[56:57] op_sel_hi:[1,0,1]
	v_pk_fma_f32 v[4:5], v[44:45], v[52:53], v[54:55] op_sel_hi:[1,0,1]
	v_add_f32_dpp v112, v112, v112 quad_perm:[1,0,3,2] row_mask:0xf bank_mask:0xf bound_ctrl:1
	v_pk_mul_f32 v[56:57], v[6:7], v[66:67]
	v_pk_mul_f32 v[54:55], v[4:5], v[64:65]
	v_add_f32_dpp v112, v112, v112 quad_perm:[2,3,0,1] row_mask:0xf bank_mask:0xf bound_ctrl:1
	v_pk_fma_f32 v[56:57], v[30:31], v[32:33], v[56:57] op_sel_hi:[1,0,1]
	v_pk_fma_f32 v[54:55], v[28:29], v[32:33], v[54:55] op_sel_hi:[1,0,1]
	v_add_f32_dpp v112, v112, v112 row_half_mirror row_mask:0xf bank_mask:0xf bound_ctrl:1
	v_pk_mul_f32 v[26:27], v[6:7], v[38:39]
	v_add_f32_dpp v34, v25, v25 row_ror:8 row_mask:0xf bank_mask:0xc
	v_add_f32_dpp v112, v112, v112 row_mirror row_mask:0xf bank_mask:0xf bound_ctrl:1
	v_pk_mul_f32 v[114:115], v[56:57], v[70:71]
	v_pk_mul_f32 v[116:117], v[50:51], v[70:71]
	v_pk_fma_f32 v[114:115], v[54:55], v[68:69], v[114:115]
	v_pk_fma_f32 v[116:117], v[48:49], v[68:69], v[116:117]
	v_pk_fma_f32 v[26:27], v[4:5], v[36:37], v[26:27]
	v_add_f32_e32 v118, v114, v115
	v_add_f32_e32 v119, v116, v117
	ds_read_b128 v[60:63], v9 offset:12352
	ds_read_b128 v[16:19], v9 offset:10752
	ds_read_b128 v[20:23], v9 offset:11520
	ds_read_b32 v24, v10 offset:12032
	ds_read_b128 v[44:47], v9 offset:11264
	ds_read_b128 v[100:103], v9 offset:10432
	v_add_f32_e32 v25, v26, v27
	v_add_f32_dpp v35, v34, v34 row_half_mirror row_mask:0xf bank_mask:0xa
	s_waitcnt lgkmcnt(6)
; __device__ void scan_block(const Params& P, int sb, unsigned char* lds) {
;     ...
;       for (int s = 0; s < SC_CH; ++s) {
;         f32x4 w4n, k4n, b4n, kh4n, r4n; float vn;
;         if (s + 1 < SC_CH) {
;           const float* qn = q + (s + 1) * SC_STEP;
;           w4n = *(const f32x4*)(qn); k4n = *(const f32x4*)(qn + 64); b4n = *(const f32x4*)(qn + 128); kh4n = *(const f32x4*)(qn + 192); r4n = *(const f32x4*)(qn + 256);
;           vn = qv[(s + 1) * SC_STEP];
;         }
;         __builtin_amdgcn_sched_barrier(0);
;         if (s > 0) {
;           const float y = dpp_allreduce16(ypart);
;           yk = (ks == ((s - 1) & 15)) ? y : yk;
;           if (((s - 1) & 15) == 15) yo[(size_t)(s - 16) * 1024] = yk;
;         }
;         const f32x2 pp = (f32x2){S[0], S[1]} * (f32x2){k4[0], k4[1]} + (f32x2){S[2], S[3]} * (f32x2){k4[2], k4[3]};
;         const f32x4 A = S * w4 + v * kh4;
;         const float ar = dpp_allreduce16(pp.x + pp.y);
;         S = A + ar * b4;
;         const f32x2 yy = (f32x2){S[0], S[1]} * (f32x2){r4[0], r4[1]} + (f32x2){S[2], S[3]} * (f32x2){r4[2], r4[3]};
;         ypart = yy.x + yy.y;
;         if (s + 1 < SC_CH) { w4 = w4n; k4 = k4n; b4 = b4n; kh4 = kh4n; r4 = r4n; v = vn; }
;       }
	v_fma_f32 v52, v119, v112, v118
	v_pk_fma_f32 v[6:7], v[50:51], v[112:113], v[56:57] op_sel_hi:[1,0,1]
	v_pk_fma_f32 v[4:5], v[48:49], v[112:113], v[54:55] op_sel_hi:[1,0,1]
	v_add_f32_dpp v52, v52, v52 quad_perm:[1,0,3,2] row_mask:0xf bank_mask:0xf bound_ctrl:1
	v_pk_mul_f32 v[56:57], v[6:7], v[74:75]
	v_pk_mul_f32 v[54:55], v[4:5], v[72:73]
	v_add_f32_dpp v52, v52, v52 quad_perm:[2,3,0,1] row_mask:0xf bank_mask:0xf bound_ctrl:1
	v_pk_fma_f32 v[56:57], v[86:87], v[92:93], v[56:57] op_sel_hi:[1,0,1]
	v_pk_fma_f32 v[54:55], v[84:85], v[92:93], v[54:55] op_sel_hi:[1,0,1]
	v_add_f32_dpp v52, v52, v52 row_half_mirror row_mask:0xf bank_mask:0xf bound_ctrl:1
	v_pk_mul_f32 v[26:27], v[6:7], v[42:43]
	v_add_f32_dpp v34, v25, v25 row_ror:8 row_mask:0xf bank_mask:0x3
	v_add_f32_dpp v52, v52, v52 row_mirror row_mask:0xf bank_mask:0xf bound_ctrl:1
	v_pk_mul_f32 v[114:115], v[56:57], v[78:79]
	v_pk_mul_f32 v[116:117], v[106:107], v[78:79]
	v_pk_fma_f32 v[114:115], v[54:55], v[76:77], v[114:115]
	v_pk_fma_f32 v[116:117], v[104:105], v[76:77], v[116:117]
	v_pk_fma_f32 v[26:27], v[4:5], v[40:41], v[26:27]
	v_add_f32_e32 v118, v114, v115
	v_add_f32_e32 v119, v116, v117
	ds_read_b128 v[68:71], v9 offset:13696
	ds_read_b128 v[64:67], v9 offset:12096
	ds_read_b128 v[28:31], v9 offset:12864
	ds_read_b32 v32, v10 offset:13376
	ds_read_b128 v[48:51], v9 offset:12608
	ds_read_b128 v[36:39], v9 offset:11776
	v_add_f32_e32 v25, v26, v27
	v_fma_f32 v112, v119, v52, v118
	v_pk_fma_f32 v[6:7], v[106:107], v[52:53], v[56:57] op_sel_hi:[1,0,1]
	v_pk_fma_f32 v[4:5], v[104:105], v[52:53], v[54:55] op_sel_hi:[1,0,1]
	v_add_f32_dpp v112, v112, v112 quad_perm:[1,0,3,2] row_mask:0xf bank_mask:0xf bound_ctrl:1
	v_pk_mul_f32 v[56:57], v[6:7], v[82:83]
	v_pk_mul_f32 v[54:55], v[4:5], v[80:81]
	v_add_f32_dpp v112, v112, v112 quad_perm:[2,3,0,1] row_mask:0xf bank_mask:0xf bound_ctrl:1
	v_pk_fma_f32 v[56:57], v[90:91], v[94:95], v[56:57] op_sel_hi:[1,0,1]
	v_pk_fma_f32 v[54:55], v[88:89], v[94:95], v[54:55] op_sel_hi:[1,0,1]
	v_add_f32_dpp v112, v112, v112 row_half_mirror row_mask:0xf bank_mask:0xf bound_ctrl:1
	v_pk_mul_f32 v[26:27], v[6:7], v[98:99]
	v_add_f32_dpp v34, v25, v25 row_ror:8 row_mask:0xf bank_mask:0xc
	v_add_f32_dpp v112, v112, v112 row_mirror row_mask:0xf bank_mask:0xf bound_ctrl:1
	v_pk_mul_f32 v[114:115], v[56:57], v[14:15]
	v_pk_mul_f32 v[116:117], v[110:111], v[14:15]
	v_pk_fma_f32 v[114:115], v[54:55], v[12:13], v[114:115]
	v_pk_fma_f32 v[116:117], v[108:109], v[12:13], v[116:117]
	v_pk_fma_f32 v[26:27], v[4:5], v[96:97], v[26:27]
	v_add_f32_e32 v118, v114, v115
	v_add_f32_e32 v119, v116, v117
	ds_read_b128 v[76:79], v9 offset:15040
	ds_read_b128 v[72:75], v9 offset:13440
	ds_read_b128 v[84:87], v9 offset:14208
	ds_read_b32 v92, v10 offset:14720
	ds_read_b128 v[104:107], v9 offset:13952
	ds_read_b128 v[40:43], v9 offset:13120
	v_add_f32_e32 v25, v26, v27
	v_add_f32_dpp v58, v34, v34 row_half_mirror row_mask:0xf bank_mask:0x5
	s_waitcnt lgkmcnt(6)
	v_fma_f32 v52, v119, v112, v118
	v_pk_fma_f32 v[6:7], v[110:111], v[112:113], v[56:57] op_sel_hi:[1,0,1]
	v_pk_fma_f32 v[4:5], v[108:109], v[112:113], v[54:55] op_sel_hi:[1,0,1]
	v_add_f32_dpp v52, v52, v52 quad_perm:[1,0,3,2] row_mask:0xf bank_mask:0xf bound_ctrl:1
	v_pk_mul_f32 v[56:57], v[6:7], v[18:19]
	v_pk_mul_f32 v[54:55], v[4:5], v[16:17]
	v_add_f32_dpp v52, v52, v52 quad_perm:[2,3,0,1] row_mask:0xf bank_mask:0xf bound_ctrl:1
	v_pk_fma_f32 v[56:57], v[22:23], v[24:25], v[56:57] op_sel_hi:[1,0,1]
	v_pk_fma_f32 v[54:55], v[20:21], v[24:25], v[54:55] op_sel_hi:[1,0,1]
	v_add_f32_dpp v52, v52, v52 row_half_mirror row_mask:0xf bank_mask:0xf bound_ctrl:1
	v_pk_mul_f32 v[26:27], v[6:7], v[102:103]
	v_add_f32_dpp v34, v25, v25 row_ror:8 row_mask:0xf bank_mask:0x3
	v_add_f32_dpp v52, v52, v52 row_mirror row_mask:0xf bank_mask:0xf bound_ctrl:1
	v_pk_mul_f32 v[114:115], v[56:57], v[62:63]
	v_pk_mul_f32 v[116:117], v[46:47], v[62:63]
	v_pk_fma_f32 v[114:115], v[54:55], v[60:61], v[114:115]
	v_pk_fma_f32 v[116:117], v[44:45], v[60:61], v[116:117]
	v_pk_fma_f32 v[26:27], v[4:5], v[100:101], v[26:27]
	v_add_f32_e32 v118, v114, v115
	v_add_f32_e32 v119, v116, v117
	ds_read_b128 v[12:15], v9 offset:16384
	ds_read_b128 v[80:83], v9 offset:14784
	ds_read_b128 v[88:91], v9 offset:15552
	ds_read_b32 v94, v10 offset:16064
	ds_read_b128 v[108:111], v9 offset:15296
	ds_read_b128 v[96:99], v9 offset:14464
	v_add_f32_e32 v25, v26, v27
	v_fma_f32 v112, v119, v52, v118
	v_pk_fma_f32 v[6:7], v[46:47], v[52:53], v[56:57] op_sel_hi:[1,0,1]
	v_pk_fma_f32 v[4:5], v[44:45], v[52:53], v[54:55] op_sel_hi:[1,0,1]
	v_add_f32_dpp v112, v112, v112 quad_perm:[1,0,3,2] row_mask:0xf bank_mask:0xf bound_ctrl:1
	v_pk_mul_f32 v[56:57], v[6:7], v[66:67]
	v_pk_mul_f32 v[54:55], v[4:5], v[64:65]
	v_add_f32_dpp v112, v112, v112 quad_perm:[2,3,0,1] row_mask:0xf bank_mask:0xf bound_ctrl:1
	v_pk_fma_f32 v[56:57], v[30:31], v[32:33], v[56:57] op_sel_hi:[1,0,1]
	v_pk_fma_f32 v[54:55], v[28:29], v[32:33], v[54:55] op_sel_hi:[1,0,1]
	v_add_f32_dpp v112, v112, v112 row_half_mirror row_mask:0xf bank_mask:0xf bound_ctrl:1
	v_pk_mul_f32 v[26:27], v[6:7], v[38:39]
	v_add_f32_dpp v34, v25, v25 row_ror:8 row_mask:0xf bank_mask:0xc
	v_add_f32_dpp v112, v112, v112 row_mirror row_mask:0xf bank_mask:0xf bound_ctrl:1
	v_pk_mul_f32 v[114:115], v[56:57], v[70:71]
	v_pk_mul_f32 v[116:117], v[50:51], v[70:71]
	v_pk_fma_f32 v[114:115], v[54:55], v[68:69], v[114:115]
	v_pk_fma_f32 v[116:117], v[48:49], v[68:69], v[116:117]
	v_pk_fma_f32 v[26:27], v[4:5], v[36:37], v[26:27]
	v_add_f32_e32 v118, v114, v115
	v_add_f32_e32 v119, v116, v117
	ds_read_b128 v[60:63], v9 offset:17728
	ds_read_b128 v[16:19], v9 offset:16128
	ds_read_b128 v[20:23], v9 offset:16896
	ds_read_b32 v24, v10 offset:17408
	ds_read_b128 v[44:47], v9 offset:16640
	ds_read_b128 v[100:103], v9 offset:15808
	v_add_f32_e32 v25, v26, v27
	v_add_f32_dpp v58, v34, v34 row_half_mirror row_mask:0xf bank_mask:0xa
	s_waitcnt lgkmcnt(6)
; __device__ void scan_block(const Params& P, int sb, unsigned char* lds) {
;     ...
;       for (int s = 0; s < SC_CH; ++s) {
;         f32x4 w4n, k4n, b4n, kh4n, r4n; float vn;
;         if (s + 1 < SC_CH) {
;           const float* qn = q + (s + 1) * SC_STEP;
;           w4n = *(const f32x4*)(qn); k4n = *(const f32x4*)(qn + 64); b4n = *(const f32x4*)(qn + 128); kh4n = *(const f32x4*)(qn + 192); r4n = *(const f32x4*)(qn + 256);
;           vn = qv[(s + 1) * SC_STEP];
;         }
;         __builtin_amdgcn_sched_barrier(0);
;         if (s > 0) {
;           const float y = dpp_allreduce16(ypart);
;           yk = (ks == ((s - 1) & 15)) ? y : yk;
;           if (((s - 1) & 15) == 15) yo[(size_t)(s - 16) * 1024] = yk;
;         }
;         const f32x2 pp = (f32x2){S[0], S[1]} * (f32x2){k4[0], k4[1]} + (f32x2){S[2], S[3]} * (f32x2){k4[2], k4[3]};
;         const f32x4 A = S * w4 + v * kh4;
;         const float ar = dpp_allreduce16(pp.x + pp.y);
;         S = A + ar * b4;
;         const f32x2 yy = (f32x2){S[0], S[1]} * (f32x2){r4[0], r4[1]} + (f32x2){S[2], S[3]} * (f32x2){r4[2], r4[3]};
;         ypart = yy.x + yy.y;
;         if (s + 1 < SC_CH) { w4 = w4n; k4 = k4n; b4 = b4n; kh4 = kh4n; r4 = r4n; v = vn; }
;       }
	v_fma_f32 v52, v119, v112, v118
	v_pk_fma_f32 v[6:7], v[50:51], v[112:113], v[56:57] op_sel_hi:[1,0,1]
	v_pk_fma_f32 v[4:5], v[48:49], v[112:113], v[54:55] op_sel_hi:[1,0,1]
	v_add_f32_dpp v52, v52, v52 quad_perm:[1,0,3,2] row_mask:0xf bank_mask:0xf bound_ctrl:1
	v_pk_mul_f32 v[56:57], v[6:7], v[74:75]
	v_pk_mul_f32 v[54:55], v[4:5], v[72:73]
	v_add_f32_dpp v52, v52, v52 quad_perm:[2,3,0,1] row_mask:0xf bank_mask:0xf bound_ctrl:1
	v_pk_fma_f32 v[56:57], v[86:87], v[92:93], v[56:57] op_sel_hi:[1,0,1]
	v_pk_fma_f32 v[54:55], v[84:85], v[92:93], v[54:55] op_sel_hi:[1,0,1]
	v_add_f32_dpp v52, v52, v52 row_half_mirror row_mask:0xf bank_mask:0xf bound_ctrl:1
	v_pk_mul_f32 v[26:27], v[6:7], v[42:43]
	v_add_f32_dpp v34, v25, v25 row_ror:8 row_mask:0xf bank_mask:0x3
	v_add_f32_dpp v52, v52, v52 row_mirror row_mask:0xf bank_mask:0xf bound_ctrl:1
	v_pk_mul_f32 v[114:115], v[56:57], v[78:79]
	v_pk_mul_f32 v[116:117], v[106:107], v[78:79]
	v_pk_fma_f32 v[114:115], v[54:55], v[76:77], v[114:115]
	v_pk_fma_f32 v[116:117], v[104:105], v[76:77], v[116:117]
	v_pk_fma_f32 v[26:27], v[4:5], v[40:41], v[26:27]
	v_add_f32_e32 v118, v114, v115
	v_add_f32_e32 v119, v116, v117
	ds_read_b128 v[68:71], v9 offset:19072
	ds_read_b128 v[64:67], v9 offset:17472
	ds_read_b128 v[28:31], v9 offset:18240
	ds_read_b32 v32, v10 offset:18752
	ds_read_b128 v[48:51], v9 offset:17984
	ds_read_b128 v[36:39], v9 offset:17152
	v_add_f32_e32 v25, v26, v27
	v_cndmask_b32_e64 v255, v35, v58, s[40:41]
	v_fma_f32 v112, v119, v52, v118
	v_pk_fma_f32 v[6:7], v[106:107], v[52:53], v[56:57] op_sel_hi:[1,0,1]
	v_pk_fma_f32 v[4:5], v[104:105], v[52:53], v[54:55] op_sel_hi:[1,0,1]
	v_add_f32_dpp v112, v112, v112 quad_perm:[1,0,3,2] row_mask:0xf bank_mask:0xf bound_ctrl:1
	v_pk_mul_f32 v[56:57], v[6:7], v[82:83]
	v_pk_mul_f32 v[54:55], v[4:5], v[80:81]
	v_add_f32_dpp v112, v112, v112 quad_perm:[2,3,0,1] row_mask:0xf bank_mask:0xf bound_ctrl:1
	v_pk_fma_f32 v[56:57], v[90:91], v[94:95], v[56:57] op_sel_hi:[1,0,1]
	v_pk_fma_f32 v[54:55], v[88:89], v[94:95], v[54:55] op_sel_hi:[1,0,1]
	v_add_f32_dpp v112, v112, v112 row_half_mirror row_mask:0xf bank_mask:0xf bound_ctrl:1
	v_pk_mul_f32 v[26:27], v[6:7], v[98:99]
	v_add_f32_dpp v34, v25, v25 row_ror:8 row_mask:0xf bank_mask:0xc
	v_add_f32_dpp v112, v112, v112 row_mirror row_mask:0xf bank_mask:0xf bound_ctrl:1
	v_pk_mul_f32 v[114:115], v[56:57], v[14:15]
	v_pk_mul_f32 v[116:117], v[110:111], v[14:15]
	v_pk_fma_f32 v[114:115], v[54:55], v[12:13], v[114:115]
	v_pk_fma_f32 v[116:117], v[108:109], v[12:13], v[116:117]
	v_pk_fma_f32 v[26:27], v[4:5], v[96:97], v[26:27]
	v_add_f32_e32 v118, v114, v115
	v_add_f32_e32 v119, v116, v117
	ds_read_b128 v[76:79], v9 offset:20416
	ds_read_b128 v[72:75], v9 offset:18816
	ds_read_b128 v[84:87], v9 offset:19584
	ds_read_b32 v92, v10 offset:20096
	ds_read_b128 v[104:107], v9 offset:19328
	ds_read_b128 v[40:43], v9 offset:18496
	v_add_f32_e32 v25, v26, v27
	v_add_f32_dpp v0, v34, v34 row_half_mirror row_mask:0xf bank_mask:0x5
	s_waitcnt lgkmcnt(6)
	v_fma_f32 v52, v119, v112, v118
	v_pk_fma_f32 v[6:7], v[110:111], v[112:113], v[56:57] op_sel_hi:[1,0,1]
	v_pk_fma_f32 v[4:5], v[108:109], v[112:113], v[54:55] op_sel_hi:[1,0,1]
	v_add_f32_dpp v52, v52, v52 quad_perm:[1,0,3,2] row_mask:0xf bank_mask:0xf bound_ctrl:1
	v_pk_mul_f32 v[56:57], v[6:7], v[18:19]
	v_pk_mul_f32 v[54:55], v[4:5], v[16:17]
	v_add_f32_dpp v52, v52, v52 quad_perm:[2,3,0,1] row_mask:0xf bank_mask:0xf bound_ctrl:1
	v_pk_fma_f32 v[56:57], v[22:23], v[24:25], v[56:57] op_sel_hi:[1,0,1]
	v_pk_fma_f32 v[54:55], v[20:21], v[24:25], v[54:55] op_sel_hi:[1,0,1]
	v_add_f32_dpp v52, v52, v52 row_half_mirror row_mask:0xf bank_mask:0xf bound_ctrl:1
	v_pk_mul_f32 v[26:27], v[6:7], v[102:103]
	v_add_f32_dpp v34, v25, v25 row_ror:8 row_mask:0xf bank_mask:0x3
	v_add_f32_dpp v52, v52, v52 row_mirror row_mask:0xf bank_mask:0xf bound_ctrl:1
	v_pk_mul_f32 v[114:115], v[56:57], v[62:63]
	v_pk_mul_f32 v[116:117], v[46:47], v[62:63]
	v_pk_fma_f32 v[114:115], v[54:55], v[60:61], v[114:115]
	v_pk_fma_f32 v[116:117], v[44:45], v[60:61], v[116:117]
	v_pk_fma_f32 v[26:27], v[4:5], v[100:101], v[26:27]
	v_add_f32_e32 v118, v114, v115
	v_add_f32_e32 v119, v116, v117
	ds_read_b128 v[12:15], v9 offset:21760
	ds_read_b128 v[80:83], v9 offset:20160
	ds_read_b128 v[88:91], v9 offset:20928
	ds_read_b32 v94, v10 offset:21440
	ds_read_b128 v[108:111], v9 offset:20672
	ds_read_b128 v[96:99], v9 offset:19840
	v_add_f32_e32 v25, v26, v27
	v_cndmask_b32_e64 v8, v58, v35, s[40:41]
	v_fma_f32 v112, v119, v52, v118
	v_pk_fma_f32 v[6:7], v[46:47], v[52:53], v[56:57] op_sel_hi:[1,0,1]
	v_pk_fma_f32 v[4:5], v[44:45], v[52:53], v[54:55] op_sel_hi:[1,0,1]
	v_add_f32_dpp v112, v112, v112 quad_perm:[1,0,3,2] row_mask:0xf bank_mask:0xf bound_ctrl:1
	v_pk_mul_f32 v[56:57], v[6:7], v[66:67]
	v_pk_mul_f32 v[54:55], v[4:5], v[64:65]
	v_add_f32_dpp v112, v112, v112 quad_perm:[2,3,0,1] row_mask:0xf bank_mask:0xf bound_ctrl:1
	v_pk_fma_f32 v[56:57], v[30:31], v[32:33], v[56:57] op_sel_hi:[1,0,1]
	v_pk_fma_f32 v[54:55], v[28:29], v[32:33], v[54:55] op_sel_hi:[1,0,1]
	v_add_f32_dpp v112, v112, v112 row_half_mirror row_mask:0xf bank_mask:0xf bound_ctrl:1
	v_pk_mul_f32 v[26:27], v[6:7], v[38:39]
	v_add_f32_dpp v34, v25, v25 row_ror:8 row_mask:0xf bank_mask:0xc
	v_add_f32_dpp v112, v112, v112 row_mirror row_mask:0xf bank_mask:0xf bound_ctrl:1
	v_pk_mul_f32 v[114:115], v[56:57], v[70:71]
	v_pk_mul_f32 v[116:117], v[50:51], v[70:71]
	v_pk_fma_f32 v[114:115], v[54:55], v[68:69], v[114:115]
	v_pk_fma_f32 v[116:117], v[48:49], v[68:69], v[116:117]
	v_pk_fma_f32 v[26:27], v[4:5], v[36:37], v[26:27]
	v_add_f32_e32 v118, v114, v115
	v_add_f32_e32 v119, v116, v117
	ds_read_b128 v[60:63], v9 offset:23104
	ds_read_b128 v[16:19], v9 offset:21504
	ds_read_b128 v[20:23], v9 offset:22272
	ds_read_b32 v24, v10 offset:22784
	ds_read_b128 v[44:47], v9 offset:22016
	ds_read_b128 v[100:103], v9 offset:21184
	v_add_f32_e32 v25, v26, v27
	v_add_f32_dpp v0, v34, v34 row_half_mirror row_mask:0xf bank_mask:0xa
	s_waitcnt lgkmcnt(6)
; __device__ void scan_block(const Params& P, int sb, unsigned char* lds) {
;     ...
;       for (int s = 0; s < SC_CH; ++s) {
;         f32x4 w4n, k4n, b4n, kh4n, r4n; float vn;
;         if (s + 1 < SC_CH) {
;           const float* qn = q + (s + 1) * SC_STEP;
;           w4n = *(const f32x4*)(qn); k4n = *(const f32x4*)(qn + 64); b4n = *(const f32x4*)(qn + 128); kh4n = *(const f32x4*)(qn + 192); r4n = *(const f32x4*)(qn + 256);
;           vn = qv[(s + 1) * SC_STEP];
;         }
;         __builtin_amdgcn_sched_barrier(0);
;         if (s > 0) {
;           const float y = dpp_allreduce16(ypart);
;           yk = (ks == ((s - 1) & 15)) ? y : yk;
;           if (((s - 1) & 15) == 15) yo[(size_t)(s - 16) * 1024] = yk;
;         }
;         const f32x2 pp = (f32x2){S[0], S[1]} * (f32x2){k4[0], k4[1]} + (f32x2){S[2], S[3]} * (f32x2){k4[2], k4[3]};
;         const f32x4 A = S * w4 + v * kh4;
;         const float ar = dpp_allreduce16(pp.x + pp.y);
;         S = A + ar * b4;
;         const f32x2 yy = (f32x2){S[0], S[1]} * (f32x2){r4[0], r4[1]} + (f32x2){S[2], S[3]} * (f32x2){r4[2], r4[3]};
;         ypart = yy.x + yy.y;
;         if (s + 1 < SC_CH) { w4 = w4n; k4 = k4n; b4 = b4n; kh4 = kh4n; r4 = r4n; v = vn; }
;       }
	v_fma_f32 v52, v119, v112, v118
	v_pk_fma_f32 v[6:7], v[50:51], v[112:113], v[56:57] op_sel_hi:[1,0,1]
	v_pk_fma_f32 v[4:5], v[48:49], v[112:113], v[54:55] op_sel_hi:[1,0,1]
	v_add_f32_dpp v52, v52, v52 quad_perm:[1,0,3,2] row_mask:0xf bank_mask:0xf bound_ctrl:1
	v_pk_mul_f32 v[56:57], v[6:7], v[74:75]
	v_pk_mul_f32 v[54:55], v[4:5], v[72:73]
	v_add_f32_dpp v52, v52, v52 quad_perm:[2,3,0,1] row_mask:0xf bank_mask:0xf bound_ctrl:1
	v_pk_fma_f32 v[56:57], v[86:87], v[92:93], v[56:57] op_sel_hi:[1,0,1]
	v_pk_fma_f32 v[54:55], v[84:85], v[92:93], v[54:55] op_sel_hi:[1,0,1]
	v_add_f32_dpp v52, v52, v52 row_half_mirror row_mask:0xf bank_mask:0xf bound_ctrl:1
	v_pk_mul_f32 v[26:27], v[6:7], v[42:43]
	v_add_f32_dpp v34, v25, v25 row_ror:8 row_mask:0xf bank_mask:0x3
	v_add_f32_dpp v52, v52, v52 row_mirror row_mask:0xf bank_mask:0xf bound_ctrl:1
	v_pk_mul_f32 v[114:115], v[56:57], v[78:79]
	v_pk_mul_f32 v[116:117], v[106:107], v[78:79]
	v_pk_fma_f32 v[114:115], v[54:55], v[76:77], v[114:115]
	v_pk_fma_f32 v[116:117], v[104:105], v[76:77], v[116:117]
	v_pk_fma_f32 v[26:27], v[4:5], v[40:41], v[26:27]
	v_add_f32_e32 v118, v114, v115
	v_add_f32_e32 v119, v116, v117
	ds_read_b128 v[68:71], v9 offset:24448
	ds_read_b128 v[64:67], v9 offset:22848
	ds_read_b128 v[28:31], v9 offset:23616
	ds_read_b32 v32, v10 offset:24128
	ds_read_b128 v[48:51], v9 offset:23360
	ds_read_b128 v[36:39], v9 offset:22528
	v_add_f32_e32 v25, v26, v27
	v_add_f32_dpp v253, v8, v255 quad_perm:[2,3,0,1] row_mask:0xf bank_mask:0xf bound_ctrl:1
	v_fma_f32 v112, v119, v52, v118
	v_pk_fma_f32 v[6:7], v[106:107], v[52:53], v[56:57] op_sel_hi:[1,0,1]
	v_pk_fma_f32 v[4:5], v[104:105], v[52:53], v[54:55] op_sel_hi:[1,0,1]
	v_add_f32_dpp v112, v112, v112 quad_perm:[1,0,3,2] row_mask:0xf bank_mask:0xf bound_ctrl:1
	v_pk_mul_f32 v[56:57], v[6:7], v[82:83]
	v_pk_mul_f32 v[54:55], v[4:5], v[80:81]
	v_add_f32_dpp v112, v112, v112 quad_perm:[2,3,0,1] row_mask:0xf bank_mask:0xf bound_ctrl:1
	v_pk_fma_f32 v[56:57], v[90:91], v[94:95], v[56:57] op_sel_hi:[1,0,1]
	v_pk_fma_f32 v[54:55], v[88:89], v[94:95], v[54:55] op_sel_hi:[1,0,1]
	v_add_f32_dpp v112, v112, v112 row_half_mirror row_mask:0xf bank_mask:0xf bound_ctrl:1
	v_pk_mul_f32 v[26:27], v[6:7], v[98:99]
	v_add_f32_dpp v34, v25, v25 row_ror:8 row_mask:0xf bank_mask:0xc
	v_add_f32_dpp v112, v112, v112 row_mirror row_mask:0xf bank_mask:0xf bound_ctrl:1
	v_pk_mul_f32 v[114:115], v[56:57], v[14:15]
	v_pk_mul_f32 v[116:117], v[110:111], v[14:15]
	v_pk_fma_f32 v[114:115], v[54:55], v[12:13], v[114:115]
	v_pk_fma_f32 v[116:117], v[108:109], v[12:13], v[116:117]
	v_pk_fma_f32 v[26:27], v[4:5], v[96:97], v[26:27]
	v_add_f32_e32 v118, v114, v115
	v_add_f32_e32 v119, v116, v117
	ds_read_b128 v[76:79], v9 offset:25792
	ds_read_b128 v[72:75], v9 offset:24192
	ds_read_b128 v[84:87], v9 offset:24960
	ds_read_b32 v92, v10 offset:25472
	ds_read_b128 v[104:107], v9 offset:24704
	ds_read_b128 v[40:43], v9 offset:23872
	v_add_f32_e32 v25, v26, v27
	v_add_f32_dpp v11, v34, v34 row_half_mirror row_mask:0xf bank_mask:0x5
	s_waitcnt lgkmcnt(6)
	v_fma_f32 v52, v119, v112, v118
	v_pk_fma_f32 v[6:7], v[110:111], v[112:113], v[56:57] op_sel_hi:[1,0,1]
	v_pk_fma_f32 v[4:5], v[108:109], v[112:113], v[54:55] op_sel_hi:[1,0,1]
	v_add_f32_dpp v52, v52, v52 quad_perm:[1,0,3,2] row_mask:0xf bank_mask:0xf bound_ctrl:1
	v_pk_mul_f32 v[56:57], v[6:7], v[18:19]
	v_pk_mul_f32 v[54:55], v[4:5], v[16:17]
	v_add_f32_dpp v52, v52, v52 quad_perm:[2,3,0,1] row_mask:0xf bank_mask:0xf bound_ctrl:1
	v_pk_fma_f32 v[56:57], v[22:23], v[24:25], v[56:57] op_sel_hi:[1,0,1]
	v_pk_fma_f32 v[54:55], v[20:21], v[24:25], v[54:55] op_sel_hi:[1,0,1]
	v_add_f32_dpp v52, v52, v52 row_half_mirror row_mask:0xf bank_mask:0xf bound_ctrl:1
	v_pk_mul_f32 v[26:27], v[6:7], v[102:103]
	v_add_f32_dpp v34, v25, v25 row_ror:8 row_mask:0xf bank_mask:0x3
	v_add_f32_dpp v52, v52, v52 row_mirror row_mask:0xf bank_mask:0xf bound_ctrl:1
	v_pk_mul_f32 v[114:115], v[56:57], v[62:63]
	v_pk_mul_f32 v[116:117], v[46:47], v[62:63]
	v_pk_fma_f32 v[114:115], v[54:55], v[60:61], v[114:115]
	v_pk_fma_f32 v[116:117], v[44:45], v[60:61], v[116:117]
	v_pk_fma_f32 v[26:27], v[4:5], v[100:101], v[26:27]
	v_add_f32_e32 v118, v114, v115
	v_add_f32_e32 v119, v116, v117
	ds_read_b128 v[12:15], v9 offset:27136
	ds_read_b128 v[80:83], v9 offset:25536
	ds_read_b128 v[88:91], v9 offset:26304
	ds_read_b32 v94, v10 offset:26816
	ds_read_b128 v[108:111], v9 offset:26048
	ds_read_b128 v[96:99], v9 offset:25216
	v_add_f32_e32 v25, v26, v27
	v_fma_f32 v112, v119, v52, v118
	v_pk_fma_f32 v[6:7], v[46:47], v[52:53], v[56:57] op_sel_hi:[1,0,1]
	v_pk_fma_f32 v[4:5], v[44:45], v[52:53], v[54:55] op_sel_hi:[1,0,1]
	v_add_f32_dpp v112, v112, v112 quad_perm:[1,0,3,2] row_mask:0xf bank_mask:0xf bound_ctrl:1
	v_pk_mul_f32 v[56:57], v[6:7], v[66:67]
	v_pk_mul_f32 v[54:55], v[4:5], v[64:65]
	v_add_f32_dpp v112, v112, v112 quad_perm:[2,3,0,1] row_mask:0xf bank_mask:0xf bound_ctrl:1
	v_pk_fma_f32 v[56:57], v[30:31], v[32:33], v[56:57] op_sel_hi:[1,0,1]
	v_pk_fma_f32 v[54:55], v[28:29], v[32:33], v[54:55] op_sel_hi:[1,0,1]
	v_add_f32_dpp v112, v112, v112 row_half_mirror row_mask:0xf bank_mask:0xf bound_ctrl:1
	v_pk_mul_f32 v[26:27], v[6:7], v[38:39]
	v_add_f32_dpp v34, v25, v25 row_ror:8 row_mask:0xf bank_mask:0xc
	v_add_f32_dpp v112, v112, v112 row_mirror row_mask:0xf bank_mask:0xf bound_ctrl:1
	v_pk_mul_f32 v[114:115], v[56:57], v[70:71]
	v_pk_mul_f32 v[116:117], v[50:51], v[70:71]
	v_pk_fma_f32 v[114:115], v[54:55], v[68:69], v[114:115]
	v_pk_fma_f32 v[116:117], v[48:49], v[68:69], v[116:117]
	v_pk_fma_f32 v[26:27], v[4:5], v[36:37], v[26:27]
	v_add_f32_e32 v118, v114, v115
	v_add_f32_e32 v119, v116, v117
	ds_read_b128 v[60:63], v9 offset:28480
	ds_read_b128 v[16:19], v9 offset:26880
	ds_read_b128 v[20:23], v9 offset:27648
	ds_read_b32 v24, v10 offset:28160
	ds_read_b128 v[44:47], v9 offset:27392
	ds_read_b128 v[100:103], v9 offset:26560
	v_add_f32_e32 v25, v26, v27
	v_add_f32_dpp v11, v34, v34 row_half_mirror row_mask:0xf bank_mask:0xa
	s_waitcnt lgkmcnt(6)
; __device__ void scan_block(const Params& P, int sb, unsigned char* lds) {
;     ...
;       for (int s = 0; s < SC_CH; ++s) {
;         f32x4 w4n, k4n, b4n, kh4n, r4n; float vn;
;         if (s + 1 < SC_CH) {
;           const float* qn = q + (s + 1) * SC_STEP;
;           w4n = *(const f32x4*)(qn); k4n = *(const f32x4*)(qn + 64); b4n = *(const f32x4*)(qn + 128); kh4n = *(const f32x4*)(qn + 192); r4n = *(const f32x4*)(qn + 256);
;           vn = qv[(s + 1) * SC_STEP];
;         }
;         __builtin_amdgcn_sched_barrier(0);
;         if (s > 0) {
;           const float y = dpp_allreduce16(ypart);
;           yk = (ks == ((s - 1) & 15)) ? y : yk;
;           if (((s - 1) & 15) == 15) yo[(size_t)(s - 16) * 1024] = yk;
;         }
;         const f32x2 pp = (f32x2){S[0], S[1]} * (f32x2){k4[0], k4[1]} + (f32x2){S[2], S[3]} * (f32x2){k4[2], k4[3]};
;         const f32x4 A = S * w4 + v * kh4;
;         const float ar = dpp_allreduce16(pp.x + pp.y);
;         S = A + ar * b4;
;         const f32x2 yy = (f32x2){S[0], S[1]} * (f32x2){r4[0], r4[1]} + (f32x2){S[2], S[3]} * (f32x2){r4[2], r4[3]};
;         ypart = yy.x + yy.y;
;         if (s + 1 < SC_CH) { w4 = w4n; k4 = k4n; b4 = b4n; kh4 = kh4n; r4 = r4n; v = vn; }
;       }
	v_fma_f32 v52, v119, v112, v118
	v_pk_fma_f32 v[6:7], v[50:51], v[112:113], v[56:57] op_sel_hi:[1,0,1]
	v_pk_fma_f32 v[4:5], v[48:49], v[112:113], v[54:55] op_sel_hi:[1,0,1]
	v_add_f32_dpp v52, v52, v52 quad_perm:[1,0,3,2] row_mask:0xf bank_mask:0xf bound_ctrl:1
	v_pk_mul_f32 v[56:57], v[6:7], v[74:75]
	v_pk_mul_f32 v[54:55], v[4:5], v[72:73]
	v_add_f32_dpp v52, v52, v52 quad_perm:[2,3,0,1] row_mask:0xf bank_mask:0xf bound_ctrl:1
	v_pk_fma_f32 v[56:57], v[86:87], v[92:93], v[56:57] op_sel_hi:[1,0,1]
	v_pk_fma_f32 v[54:55], v[84:85], v[92:93], v[54:55] op_sel_hi:[1,0,1]
	v_add_f32_dpp v52, v52, v52 row_half_mirror row_mask:0xf bank_mask:0xf bound_ctrl:1
	v_pk_mul_f32 v[26:27], v[6:7], v[42:43]
	v_add_f32_dpp v34, v25, v25 row_ror:8 row_mask:0xf bank_mask:0x3
	v_add_f32_dpp v52, v52, v52 row_mirror row_mask:0xf bank_mask:0xf bound_ctrl:1
	v_pk_mul_f32 v[114:115], v[56:57], v[78:79]
	v_pk_mul_f32 v[116:117], v[106:107], v[78:79]
	v_pk_fma_f32 v[114:115], v[54:55], v[76:77], v[114:115]
	v_pk_fma_f32 v[116:117], v[104:105], v[76:77], v[116:117]
	v_pk_fma_f32 v[26:27], v[4:5], v[40:41], v[26:27]
	v_add_f32_e32 v118, v114, v115
	v_add_f32_e32 v119, v116, v117
	ds_read_b128 v[68:71], v9 offset:29824
	ds_read_b128 v[64:67], v9 offset:28224
	ds_read_b128 v[28:31], v9 offset:28992
	ds_read_b32 v32, v10 offset:29504
	ds_read_b128 v[48:51], v9 offset:28736
	ds_read_b128 v[36:39], v9 offset:27904
	v_add_f32_e32 v25, v26, v27
	v_cndmask_b32_e64 v255, v0, v11, s[40:41]
	v_fma_f32 v112, v119, v52, v118
	v_pk_fma_f32 v[6:7], v[106:107], v[52:53], v[56:57] op_sel_hi:[1,0,1]
	v_pk_fma_f32 v[4:5], v[104:105], v[52:53], v[54:55] op_sel_hi:[1,0,1]
	v_add_f32_dpp v112, v112, v112 quad_perm:[1,0,3,2] row_mask:0xf bank_mask:0xf bound_ctrl:1
	v_pk_mul_f32 v[56:57], v[6:7], v[82:83]
	v_pk_mul_f32 v[54:55], v[4:5], v[80:81]
	v_add_f32_dpp v112, v112, v112 quad_perm:[2,3,0,1] row_mask:0xf bank_mask:0xf bound_ctrl:1
	v_pk_fma_f32 v[56:57], v[90:91], v[94:95], v[56:57] op_sel_hi:[1,0,1]
	v_pk_fma_f32 v[54:55], v[88:89], v[94:95], v[54:55] op_sel_hi:[1,0,1]
	v_add_f32_dpp v112, v112, v112 row_half_mirror row_mask:0xf bank_mask:0xf bound_ctrl:1
	v_pk_mul_f32 v[26:27], v[6:7], v[98:99]
	v_add_f32_dpp v34, v25, v25 row_ror:8 row_mask:0xf bank_mask:0xc
	v_add_f32_dpp v112, v112, v112 row_mirror row_mask:0xf bank_mask:0xf bound_ctrl:1
	v_pk_mul_f32 v[114:115], v[56:57], v[14:15]
	v_pk_mul_f32 v[116:117], v[110:111], v[14:15]
	v_pk_fma_f32 v[114:115], v[54:55], v[12:13], v[114:115]
	v_pk_fma_f32 v[116:117], v[108:109], v[12:13], v[116:117]
	v_pk_fma_f32 v[26:27], v[4:5], v[96:97], v[26:27]
	v_add_f32_e32 v118, v114, v115
	v_add_f32_e32 v119, v116, v117
	ds_read_b128 v[76:79], v9 offset:31168
	ds_read_b128 v[72:75], v9 offset:29568
	ds_read_b128 v[84:87], v9 offset:30336
	ds_read_b32 v92, v10 offset:30848
	ds_read_b128 v[104:107], v9 offset:30080
	ds_read_b128 v[40:43], v9 offset:29248
	v_add_f32_e32 v25, v26, v27
	v_add_f32_dpp v35, v34, v34 row_half_mirror row_mask:0xf bank_mask:0x5
	s_waitcnt lgkmcnt(6)
	v_fma_f32 v52, v119, v112, v118
	v_pk_fma_f32 v[6:7], v[110:111], v[112:113], v[56:57] op_sel_hi:[1,0,1]
	v_pk_fma_f32 v[4:5], v[108:109], v[112:113], v[54:55] op_sel_hi:[1,0,1]
	v_add_f32_dpp v52, v52, v52 quad_perm:[1,0,3,2] row_mask:0xf bank_mask:0xf bound_ctrl:1
	v_pk_mul_f32 v[56:57], v[6:7], v[18:19]
	v_pk_mul_f32 v[54:55], v[4:5], v[16:17]
	v_add_f32_dpp v52, v52, v52 quad_perm:[2,3,0,1] row_mask:0xf bank_mask:0xf bound_ctrl:1
	v_pk_fma_f32 v[56:57], v[22:23], v[24:25], v[56:57] op_sel_hi:[1,0,1]
	v_pk_fma_f32 v[54:55], v[20:21], v[24:25], v[54:55] op_sel_hi:[1,0,1]
	v_add_f32_dpp v52, v52, v52 row_half_mirror row_mask:0xf bank_mask:0xf bound_ctrl:1
	v_pk_mul_f32 v[26:27], v[6:7], v[102:103]
	v_add_f32_dpp v34, v25, v25 row_ror:8 row_mask:0xf bank_mask:0x3
	v_add_f32_dpp v52, v52, v52 row_mirror row_mask:0xf bank_mask:0xf bound_ctrl:1
	v_pk_mul_f32 v[114:115], v[56:57], v[62:63]
	v_pk_mul_f32 v[116:117], v[46:47], v[62:63]
	v_pk_fma_f32 v[114:115], v[54:55], v[60:61], v[114:115]
	v_pk_fma_f32 v[116:117], v[44:45], v[60:61], v[116:117]
	v_pk_fma_f32 v[26:27], v[4:5], v[100:101], v[26:27]
	v_add_f32_e32 v118, v114, v115
	v_add_f32_e32 v119, v116, v117
	ds_read_b128 v[12:15], v9 offset:32512
	ds_read_b128 v[80:83], v9 offset:30912
	ds_read_b128 v[88:91], v9 offset:31680
	ds_read_b32 v94, v10 offset:32192
	ds_read_b128 v[108:111], v9 offset:31424
	ds_read_b128 v[96:99], v9 offset:30592
	v_add_f32_e32 v25, v26, v27
	v_cndmask_b32_e64 v8, v11, v0, s[40:41]
	v_fma_f32 v112, v119, v52, v118
	v_pk_fma_f32 v[6:7], v[46:47], v[52:53], v[56:57] op_sel_hi:[1,0,1]
	v_pk_fma_f32 v[4:5], v[44:45], v[52:53], v[54:55] op_sel_hi:[1,0,1]
	v_add_f32_dpp v112, v112, v112 quad_perm:[1,0,3,2] row_mask:0xf bank_mask:0xf bound_ctrl:1
	v_pk_mul_f32 v[56:57], v[6:7], v[66:67]
	v_pk_mul_f32 v[54:55], v[4:5], v[64:65]
	v_add_f32_dpp v112, v112, v112 quad_perm:[2,3,0,1] row_mask:0xf bank_mask:0xf bound_ctrl:1
	v_pk_fma_f32 v[56:57], v[30:31], v[32:33], v[56:57] op_sel_hi:[1,0,1]
	v_pk_fma_f32 v[54:55], v[28:29], v[32:33], v[54:55] op_sel_hi:[1,0,1]
	v_add_f32_dpp v112, v112, v112 row_half_mirror row_mask:0xf bank_mask:0xf bound_ctrl:1
	v_pk_mul_f32 v[26:27], v[6:7], v[38:39]
	v_add_f32_dpp v34, v25, v25 row_ror:8 row_mask:0xf bank_mask:0xc
	v_add_f32_dpp v112, v112, v112 row_mirror row_mask:0xf bank_mask:0xf bound_ctrl:1
	v_pk_mul_f32 v[114:115], v[56:57], v[70:71]
	v_pk_mul_f32 v[116:117], v[50:51], v[70:71]
	v_pk_fma_f32 v[114:115], v[54:55], v[68:69], v[114:115]
	v_pk_fma_f32 v[116:117], v[48:49], v[68:69], v[116:117]
	v_pk_fma_f32 v[26:27], v[4:5], v[36:37], v[26:27]
	v_add_f32_e32 v118, v114, v115
	v_add_f32_e32 v119, v116, v117
	ds_read_b128 v[60:63], v9 offset:33856
	ds_read_b128 v[16:19], v9 offset:32256
	ds_read_b128 v[20:23], v9 offset:33024
	ds_read_b32 v24, v10 offset:33536
	ds_read_b128 v[44:47], v9 offset:32768
	ds_read_b128 v[100:103], v9 offset:31936
	v_add_f32_e32 v25, v26, v27
	v_add_f32_dpp v35, v34, v34 row_half_mirror row_mask:0xf bank_mask:0xa
	s_waitcnt lgkmcnt(6)
; __device__ void scan_block(const Params& P, int sb, unsigned char* lds) {
;     ...
;       for (int s = 0; s < SC_CH; ++s) {
;         f32x4 w4n, k4n, b4n, kh4n, r4n; float vn;
;         if (s + 1 < SC_CH) {
;           const float* qn = q + (s + 1) * SC_STEP;
;           w4n = *(const f32x4*)(qn); k4n = *(const f32x4*)(qn + 64); b4n = *(const f32x4*)(qn + 128); kh4n = *(const f32x4*)(qn + 192); r4n = *(const f32x4*)(qn + 256);
;           vn = qv[(s + 1) * SC_STEP];
;         }
;         __builtin_amdgcn_sched_barrier(0);
;         if (s > 0) {
;           const float y = dpp_allreduce16(ypart);
;           yk = (ks == ((s - 1) & 15)) ? y : yk;
;           if (((s - 1) & 15) == 15) yo[(size_t)(s - 16) * 1024] = yk;
;         }
;         const f32x2 pp = (f32x2){S[0], S[1]} * (f32x2){k4[0], k4[1]} + (f32x2){S[2], S[3]} * (f32x2){k4[2], k4[3]};
;         const f32x4 A = S * w4 + v * kh4;
;         const float ar = dpp_allreduce16(pp.x + pp.y);
;         S = A + ar * b4;
;         const f32x2 yy = (f32x2){S[0], S[1]} * (f32x2){r4[0], r4[1]} + (f32x2){S[2], S[3]} * (f32x2){r4[2], r4[3]};
;         ypart = yy.x + yy.y;
;         if (s + 1 < SC_CH) { w4 = w4n; k4 = k4n; b4 = b4n; kh4 = kh4n; r4 = r4n; v = vn; }
;       }
	v_fma_f32 v52, v119, v112, v118
	v_pk_fma_f32 v[6:7], v[50:51], v[112:113], v[56:57] op_sel_hi:[1,0,1]
	v_pk_fma_f32 v[4:5], v[48:49], v[112:113], v[54:55] op_sel_hi:[1,0,1]
	v_add_f32_dpp v52, v52, v52 quad_perm:[1,0,3,2] row_mask:0xf bank_mask:0xf bound_ctrl:1
	v_pk_mul_f32 v[56:57], v[6:7], v[74:75]
	v_pk_mul_f32 v[54:55], v[4:5], v[72:73]
	v_add_f32_dpp v52, v52, v52 quad_perm:[2,3,0,1] row_mask:0xf bank_mask:0xf bound_ctrl:1
	v_pk_fma_f32 v[56:57], v[86:87], v[92:93], v[56:57] op_sel_hi:[1,0,1]
	v_pk_fma_f32 v[54:55], v[84:85], v[92:93], v[54:55] op_sel_hi:[1,0,1]
	v_add_f32_dpp v52, v52, v52 row_half_mirror row_mask:0xf bank_mask:0xf bound_ctrl:1
	v_pk_mul_f32 v[26:27], v[6:7], v[42:43]
	v_add_f32_dpp v34, v25, v25 row_ror:8 row_mask:0xf bank_mask:0x3
	v_add_f32_dpp v52, v52, v52 row_mirror row_mask:0xf bank_mask:0xf bound_ctrl:1
	v_pk_mul_f32 v[114:115], v[56:57], v[78:79]
	v_pk_mul_f32 v[116:117], v[106:107], v[78:79]
	v_pk_fma_f32 v[114:115], v[54:55], v[76:77], v[114:115]
	v_pk_fma_f32 v[116:117], v[104:105], v[76:77], v[116:117]
	v_pk_fma_f32 v[26:27], v[4:5], v[40:41], v[26:27]
	v_add_f32_e32 v118, v114, v115
	v_add_f32_e32 v119, v116, v117
	ds_read_b128 v[68:71], v9 offset:35200
	ds_read_b128 v[64:67], v9 offset:33600
	ds_read_b128 v[28:31], v9 offset:34368
	ds_read_b32 v32, v10 offset:34880
	ds_read_b128 v[48:51], v9 offset:34112
	ds_read_b128 v[36:39], v9 offset:33280
	v_add_f32_e32 v25, v26, v27
	v_add_f32_dpp v254, v8, v255 quad_perm:[2,3,0,1] row_mask:0xf bank_mask:0xf bound_ctrl:1
	v_fma_f32 v112, v119, v52, v118
	v_pk_fma_f32 v[6:7], v[106:107], v[52:53], v[56:57] op_sel_hi:[1,0,1]
	v_pk_fma_f32 v[4:5], v[104:105], v[52:53], v[54:55] op_sel_hi:[1,0,1]
	v_add_f32_dpp v112, v112, v112 quad_perm:[1,0,3,2] row_mask:0xf bank_mask:0xf bound_ctrl:1
	v_pk_mul_f32 v[56:57], v[6:7], v[82:83]
	v_pk_mul_f32 v[54:55], v[4:5], v[80:81]
	v_add_f32_dpp v112, v112, v112 quad_perm:[2,3,0,1] row_mask:0xf bank_mask:0xf bound_ctrl:1
	v_pk_fma_f32 v[56:57], v[90:91], v[94:95], v[56:57] op_sel_hi:[1,0,1]
	v_pk_fma_f32 v[54:55], v[88:89], v[94:95], v[54:55] op_sel_hi:[1,0,1]
	v_add_f32_dpp v112, v112, v112 row_half_mirror row_mask:0xf bank_mask:0xf bound_ctrl:1
	v_pk_mul_f32 v[26:27], v[6:7], v[98:99]
	v_add_f32_dpp v34, v25, v25 row_ror:8 row_mask:0xf bank_mask:0xc
	v_add_f32_dpp v112, v112, v112 row_mirror row_mask:0xf bank_mask:0xf bound_ctrl:1
	v_pk_mul_f32 v[114:115], v[56:57], v[14:15]
	v_pk_mul_f32 v[116:117], v[110:111], v[14:15]
	v_pk_fma_f32 v[114:115], v[54:55], v[12:13], v[114:115]
	v_pk_fma_f32 v[116:117], v[108:109], v[12:13], v[116:117]
	v_pk_fma_f32 v[26:27], v[4:5], v[96:97], v[26:27]
	v_add_f32_e32 v118, v114, v115
	v_add_f32_e32 v119, v116, v117
	ds_read_b128 v[76:79], v9 offset:36544
	ds_read_b128 v[72:75], v9 offset:34944
	ds_read_b128 v[84:87], v9 offset:35712
	ds_read_b32 v92, v10 offset:36224
	ds_read_b128 v[104:107], v9 offset:35456
	ds_read_b128 v[40:43], v9 offset:34624
	v_add_f32_e32 v25, v26, v27
	v_add_f32_dpp v58, v34, v34 row_half_mirror row_mask:0xf bank_mask:0x5
	s_waitcnt lgkmcnt(6)
	v_fma_f32 v52, v119, v112, v118
	v_pk_fma_f32 v[6:7], v[110:111], v[112:113], v[56:57] op_sel_hi:[1,0,1]
	v_pk_fma_f32 v[4:5], v[108:109], v[112:113], v[54:55] op_sel_hi:[1,0,1]
	v_add_f32_dpp v52, v52, v52 quad_perm:[1,0,3,2] row_mask:0xf bank_mask:0xf bound_ctrl:1
	v_pk_mul_f32 v[56:57], v[6:7], v[18:19]
	v_pk_mul_f32 v[54:55], v[4:5], v[16:17]
	v_add_f32_dpp v52, v52, v52 quad_perm:[2,3,0,1] row_mask:0xf bank_mask:0xf bound_ctrl:1
	v_pk_fma_f32 v[56:57], v[22:23], v[24:25], v[56:57] op_sel_hi:[1,0,1]
	v_pk_fma_f32 v[54:55], v[20:21], v[24:25], v[54:55] op_sel_hi:[1,0,1]
	v_add_f32_dpp v52, v52, v52 row_half_mirror row_mask:0xf bank_mask:0xf bound_ctrl:1
	v_pk_mul_f32 v[26:27], v[6:7], v[102:103]
	v_add_f32_dpp v34, v25, v25 row_ror:8 row_mask:0xf bank_mask:0x3
	v_add_f32_dpp v52, v52, v52 row_mirror row_mask:0xf bank_mask:0xf bound_ctrl:1
	v_pk_mul_f32 v[114:115], v[56:57], v[62:63]
	v_pk_mul_f32 v[116:117], v[46:47], v[62:63]
	v_pk_fma_f32 v[114:115], v[54:55], v[60:61], v[114:115]
	v_pk_fma_f32 v[116:117], v[44:45], v[60:61], v[116:117]
	v_pk_fma_f32 v[26:27], v[4:5], v[100:101], v[26:27]
	v_add_f32_e32 v118, v114, v115
	v_add_f32_e32 v119, v116, v117
	ds_read_b128 v[12:15], v9 offset:37888
	ds_read_b128 v[80:83], v9 offset:36288
	ds_read_b128 v[88:91], v9 offset:37056
	ds_read_b32 v94, v10 offset:37568
	ds_read_b128 v[108:111], v9 offset:36800
	ds_read_b128 v[96:99], v9 offset:35968
	v_add_f32_e32 v25, v26, v27
	v_cndmask_b32_e64 v255, v253, v254, s[42:43]
	v_fma_f32 v112, v119, v52, v118
	v_pk_fma_f32 v[6:7], v[46:47], v[52:53], v[56:57] op_sel_hi:[1,0,1]
	v_pk_fma_f32 v[4:5], v[44:45], v[52:53], v[54:55] op_sel_hi:[1,0,1]
	v_add_f32_dpp v112, v112, v112 quad_perm:[1,0,3,2] row_mask:0xf bank_mask:0xf bound_ctrl:1
	v_pk_mul_f32 v[56:57], v[6:7], v[66:67]
	v_pk_mul_f32 v[54:55], v[4:5], v[64:65]
	v_add_f32_dpp v112, v112, v112 quad_perm:[2,3,0,1] row_mask:0xf bank_mask:0xf bound_ctrl:1
	v_pk_fma_f32 v[56:57], v[30:31], v[32:33], v[56:57] op_sel_hi:[1,0,1]
	v_pk_fma_f32 v[54:55], v[28:29], v[32:33], v[54:55] op_sel_hi:[1,0,1]
	v_add_f32_dpp v112, v112, v112 row_half_mirror row_mask:0xf bank_mask:0xf bound_ctrl:1
	v_pk_mul_f32 v[26:27], v[6:7], v[38:39]
	v_add_f32_dpp v34, v25, v25 row_ror:8 row_mask:0xf bank_mask:0xc
	v_add_f32_dpp v112, v112, v112 row_mirror row_mask:0xf bank_mask:0xf bound_ctrl:1
	v_pk_mul_f32 v[114:115], v[56:57], v[70:71]
	v_pk_mul_f32 v[116:117], v[50:51], v[70:71]
	v_pk_fma_f32 v[114:115], v[54:55], v[68:69], v[114:115]
	v_pk_fma_f32 v[116:117], v[48:49], v[68:69], v[116:117]
	v_pk_fma_f32 v[26:27], v[4:5], v[36:37], v[26:27]
	v_add_f32_e32 v118, v114, v115
	v_add_f32_e32 v119, v116, v117
	ds_read_b128 v[60:63], v9 offset:39232
	ds_read_b128 v[16:19], v9 offset:37632
	ds_read_b128 v[20:23], v9 offset:38400
	ds_read_b32 v24, v10 offset:38912
	ds_read_b128 v[44:47], v9 offset:38144
	ds_read_b128 v[100:103], v9 offset:37312
	v_add_f32_e32 v25, v26, v27
	v_add_f32_dpp v58, v34, v34 row_half_mirror row_mask:0xf bank_mask:0xa
	s_waitcnt lgkmcnt(6)
; __device__ void scan_block(const Params& P, int sb, unsigned char* lds) {
;     ...
;       for (int s = 0; s < SC_CH; ++s) {
;         f32x4 w4n, k4n, b4n, kh4n, r4n; float vn;
;         if (s + 1 < SC_CH) {
;           const float* qn = q + (s + 1) * SC_STEP;
;           w4n = *(const f32x4*)(qn); k4n = *(const f32x4*)(qn + 64); b4n = *(const f32x4*)(qn + 128); kh4n = *(const f32x4*)(qn + 192); r4n = *(const f32x4*)(qn + 256);
;           vn = qv[(s + 1) * SC_STEP];
;         }
;         __builtin_amdgcn_sched_barrier(0);
;         if (s > 0) {
;           const float y = dpp_allreduce16(ypart);
;           yk = (ks == ((s - 1) & 15)) ? y : yk;
;           if (((s - 1) & 15) == 15) yo[(size_t)(s - 16) * 1024] = yk;
;         }
;         const f32x2 pp = (f32x2){S[0], S[1]} * (f32x2){k4[0], k4[1]} + (f32x2){S[2], S[3]} * (f32x2){k4[2], k4[3]};
;         const f32x4 A = S * w4 + v * kh4;
;         const float ar = dpp_allreduce16(pp.x + pp.y);
;         S = A + ar * b4;
;         const f32x2 yy = (f32x2){S[0], S[1]} * (f32x2){r4[0], r4[1]} + (f32x2){S[2], S[3]} * (f32x2){r4[2], r4[3]};
;         ypart = yy.x + yy.y;
;         if (s + 1 < SC_CH) { w4 = w4n; k4 = k4n; b4 = b4n; kh4 = kh4n; r4 = r4n; v = vn; }
;       }
	v_fma_f32 v52, v119, v112, v118
	v_pk_fma_f32 v[6:7], v[50:51], v[112:113], v[56:57] op_sel_hi:[1,0,1]
	v_pk_fma_f32 v[4:5], v[48:49], v[112:113], v[54:55] op_sel_hi:[1,0,1]
	v_add_f32_dpp v52, v52, v52 quad_perm:[1,0,3,2] row_mask:0xf bank_mask:0xf bound_ctrl:1
	v_pk_mul_f32 v[56:57], v[6:7], v[74:75]
	v_pk_mul_f32 v[54:55], v[4:5], v[72:73]
	v_add_f32_dpp v52, v52, v52 quad_perm:[2,3,0,1] row_mask:0xf bank_mask:0xf bound_ctrl:1
	v_pk_fma_f32 v[56:57], v[86:87], v[92:93], v[56:57] op_sel_hi:[1,0,1]
	v_pk_fma_f32 v[54:55], v[84:85], v[92:93], v[54:55] op_sel_hi:[1,0,1]
	v_add_f32_dpp v52, v52, v52 row_half_mirror row_mask:0xf bank_mask:0xf bound_ctrl:1
	v_pk_mul_f32 v[26:27], v[6:7], v[42:43]
	v_add_f32_dpp v34, v25, v25 row_ror:8 row_mask:0xf bank_mask:0x3
	v_add_f32_dpp v52, v52, v52 row_mirror row_mask:0xf bank_mask:0xf bound_ctrl:1
	v_pk_mul_f32 v[114:115], v[56:57], v[78:79]
	v_pk_mul_f32 v[116:117], v[106:107], v[78:79]
	v_pk_fma_f32 v[114:115], v[54:55], v[76:77], v[114:115]
	v_pk_fma_f32 v[116:117], v[104:105], v[76:77], v[116:117]
	v_pk_fma_f32 v[26:27], v[4:5], v[40:41], v[26:27]
	v_add_f32_e32 v118, v114, v115
	v_add_f32_e32 v119, v116, v117
	ds_read_b128 v[68:71], v9 offset:40576
	ds_read_b128 v[64:67], v9 offset:38976
	ds_read_b128 v[28:31], v9 offset:39744
	ds_read_b32 v32, v10 offset:40256
	ds_read_b128 v[48:51], v9 offset:39488
	ds_read_b128 v[36:39], v9 offset:38656
	v_add_f32_e32 v25, v26, v27
	v_cndmask_b32_e64 v8, v254, v253, s[42:43]
	v_fma_f32 v112, v119, v52, v118
	v_pk_fma_f32 v[6:7], v[106:107], v[52:53], v[56:57] op_sel_hi:[1,0,1]
	v_pk_fma_f32 v[4:5], v[104:105], v[52:53], v[54:55] op_sel_hi:[1,0,1]
	v_add_f32_dpp v112, v112, v112 quad_perm:[1,0,3,2] row_mask:0xf bank_mask:0xf bound_ctrl:1
	v_pk_mul_f32 v[56:57], v[6:7], v[82:83]
	v_pk_mul_f32 v[54:55], v[4:5], v[80:81]
	v_add_f32_dpp v112, v112, v112 quad_perm:[2,3,0,1] row_mask:0xf bank_mask:0xf bound_ctrl:1
	v_pk_fma_f32 v[56:57], v[90:91], v[94:95], v[56:57] op_sel_hi:[1,0,1]
	v_pk_fma_f32 v[54:55], v[88:89], v[94:95], v[54:55] op_sel_hi:[1,0,1]
	v_add_f32_dpp v112, v112, v112 row_half_mirror row_mask:0xf bank_mask:0xf bound_ctrl:1
	v_pk_mul_f32 v[26:27], v[6:7], v[98:99]
	v_add_f32_dpp v34, v25, v25 row_ror:8 row_mask:0xf bank_mask:0xc
	v_add_f32_dpp v112, v112, v112 row_mirror row_mask:0xf bank_mask:0xf bound_ctrl:1
	v_pk_mul_f32 v[114:115], v[56:57], v[14:15]
	v_pk_mul_f32 v[116:117], v[110:111], v[14:15]
	v_pk_fma_f32 v[114:115], v[54:55], v[12:13], v[114:115]
	v_pk_fma_f32 v[116:117], v[108:109], v[12:13], v[116:117]
	v_pk_fma_f32 v[26:27], v[4:5], v[96:97], v[26:27]
	v_add_f32_e32 v118, v114, v115
	v_add_f32_e32 v119, v116, v117
	ds_read_b128 v[76:79], v9 offset:41920
	ds_read_b128 v[72:75], v9 offset:40320
	ds_read_b128 v[84:87], v9 offset:41088
	ds_read_b32 v92, v10 offset:41600
	ds_read_b128 v[104:107], v9 offset:40832
	ds_read_b128 v[40:43], v9 offset:40000
	v_add_f32_e32 v25, v26, v27
	v_add_f32_dpp v0, v34, v34 row_half_mirror row_mask:0xf bank_mask:0x5
	s_waitcnt lgkmcnt(8)
	v_fma_f32 v52, v119, v112, v118
	v_pk_fma_f32 v[6:7], v[110:111], v[112:113], v[56:57] op_sel_hi:[1,0,1]
	v_pk_fma_f32 v[4:5], v[108:109], v[112:113], v[54:55] op_sel_hi:[1,0,1]
	v_add_f32_dpp v52, v52, v52 quad_perm:[1,0,3,2] row_mask:0xf bank_mask:0xf bound_ctrl:1
	v_pk_mul_f32 v[56:57], v[6:7], v[18:19]
	v_pk_mul_f32 v[54:55], v[4:5], v[16:17]
	v_add_f32_dpp v52, v52, v52 quad_perm:[2,3,0,1] row_mask:0xf bank_mask:0xf bound_ctrl:1
	v_pk_fma_f32 v[56:57], v[22:23], v[24:25], v[56:57] op_sel_hi:[1,0,1]
	v_pk_fma_f32 v[54:55], v[20:21], v[24:25], v[54:55] op_sel_hi:[1,0,1]
	v_add_f32_dpp v52, v52, v52 row_half_mirror row_mask:0xf bank_mask:0xf bound_ctrl:1
	v_pk_mul_f32 v[26:27], v[6:7], v[102:103]
	v_add_f32_dpp v34, v25, v25 row_ror:8 row_mask:0xf bank_mask:0x3
	v_add_f32_dpp v52, v52, v52 row_mirror row_mask:0xf bank_mask:0xf bound_ctrl:1
	v_pk_mul_f32 v[114:115], v[56:57], v[62:63]
	v_pk_mul_f32 v[116:117], v[46:47], v[62:63]
	v_pk_fma_f32 v[114:115], v[54:55], v[60:61], v[114:115]
	v_pk_fma_f32 v[116:117], v[44:45], v[60:61], v[116:117]
	v_pk_fma_f32 v[26:27], v[4:5], v[100:101], v[26:27]
	v_add_f32_e32 v118, v114, v115
	v_add_f32_e32 v119, v116, v117
	ds_read_b128 v[80:83], v9 offset:41664
	ds_read_b128 v[88:91], v9 offset:42432
	ds_read_b32 v94, v10 offset:42944
	ds_read_b128 v[108:111], v9 offset:42176
	ds_read_b128 v[96:99], v9 offset:41344
	ds_read_b128 v[100:103], v9 offset:42688
	v_add_f32_e32 v25, v26, v27
	v_add_f32_dpp v33, v8, v255 quad_perm:[1,0,3,2] row_mask:0xf bank_mask:0xf bound_ctrl:1
	v_fma_f32 v112, v119, v52, v118
	v_pk_fma_f32 v[6:7], v[46:47], v[52:53], v[56:57] op_sel_hi:[1,0,1]
	v_pk_fma_f32 v[4:5], v[44:45], v[52:53], v[54:55] op_sel_hi:[1,0,1]
	v_add_f32_dpp v112, v112, v112 quad_perm:[1,0,3,2] row_mask:0xf bank_mask:0xf bound_ctrl:1
	v_pk_mul_f32 v[56:57], v[6:7], v[66:67]
	v_pk_mul_f32 v[54:55], v[4:5], v[64:65]
	v_add_f32_dpp v112, v112, v112 quad_perm:[2,3,0,1] row_mask:0xf bank_mask:0xf bound_ctrl:1
	v_pk_fma_f32 v[56:57], v[30:31], v[32:33], v[56:57] op_sel_hi:[1,0,1]
	v_pk_fma_f32 v[54:55], v[28:29], v[32:33], v[54:55] op_sel_hi:[1,0,1]
	s_waitcnt lgkmcnt(0)
	s_barrier
; __device__ void scan_block(const Params& P, int sb, unsigned char* lds) {
;     ...
;       for (int s = 0; s < SC_CH; ++s) {
;         f32x4 w4n, k4n, b4n, kh4n, r4n; float vn;
;         if (s + 1 < SC_CH) {
;           const float* qn = q + (s + 1) * SC_STEP;
;           w4n = *(const f32x4*)(qn); k4n = *(const f32x4*)(qn + 64); b4n = *(const f32x4*)(qn + 128); kh4n = *(const f32x4*)(qn + 192); r4n = *(const f32x4*)(qn + 256);
;           vn = qv[(s + 1) * SC_STEP];
;         }
;         __builtin_amdgcn_sched_barrier(0);
;         if (s > 0) {
;           const float y = dpp_allreduce16(ypart);
;           yk = (ks == ((s - 1) & 15)) ? y : yk;
;           if (((s - 1) & 15) == 15) yo[(size_t)(s - 16) * 1024] = yk;
;         }
;         const f32x2 pp = (f32x2){S[0], S[1]} * (f32x2){k4[0], k4[1]} + (f32x2){S[2], S[3]} * (f32x2){k4[2], k4[3]};
;         const f32x4 A = S * w4 + v * kh4;
;         const float ar = dpp_allreduce16(pp.x + pp.y);
;         S = A + ar * b4;
;         const f32x2 yy = (f32x2){S[0], S[1]} * (f32x2){r4[0], r4[1]} + (f32x2){S[2], S[3]} * (f32x2){r4[2], r4[3]};
;         ypart = yy.x + yy.y;
;         if (s + 1 < SC_CH) { w4 = w4n; k4 = k4n; b4 = b4n; kh4 = kh4n; r4 = r4n; v = vn; }
;       }
;       { const float y = dpp_allreduce16(ypart); yk = (ks == 15) ? y : yk; yo[(size_t)16 * 1024] = yk; }
;       __syncthreads();
	v_xor_b32_e32 v9, 0xa800, v9
	v_xor_b32_e32 v10, 0xa800, v10
	ds_read_b128 v[12:15], v9 offset:256
	ds_read_b128 v[60:63], v9 offset:1600
	v_add_f32_dpp v112, v112, v112 row_half_mirror row_mask:0xf bank_mask:0xf bound_ctrl:1
	v_pk_mul_f32 v[26:27], v[6:7], v[38:39]
	v_add_f32_dpp v34, v25, v25 row_ror:8 row_mask:0xf bank_mask:0xc
	v_add_f32_dpp v112, v112, v112 row_mirror row_mask:0xf bank_mask:0xf bound_ctrl:1
	v_pk_mul_f32 v[114:115], v[56:57], v[70:71]
	v_pk_mul_f32 v[116:117], v[50:51], v[70:71]
	v_pk_fma_f32 v[114:115], v[54:55], v[68:69], v[114:115]
	v_pk_fma_f32 v[116:117], v[48:49], v[68:69], v[116:117]
	v_pk_fma_f32 v[26:27], v[4:5], v[36:37], v[26:27]
	v_add_f32_e32 v118, v114, v115
	v_add_f32_e32 v119, v116, v117
	ds_read_b128 v[16:19], v9 offset:0
	ds_read_b128 v[20:23], v9 offset:768
	ds_read_b32 v24, v10 offset:1280
	ds_read_b128 v[44:47], v9 offset:512
	v_add_f32_e32 v25, v26, v27
	v_add_f32_dpp v0, v34, v34 row_half_mirror row_mask:0xf bank_mask:0xa
	s_waitcnt lgkmcnt(12)
	v_fma_f32 v52, v119, v112, v118
	v_pk_fma_f32 v[6:7], v[50:51], v[112:113], v[56:57] op_sel_hi:[1,0,1]
	v_pk_fma_f32 v[4:5], v[48:49], v[112:113], v[54:55] op_sel_hi:[1,0,1]
	v_add_f32_dpp v52, v52, v52 quad_perm:[1,0,3,2] row_mask:0xf bank_mask:0xf bound_ctrl:1
	v_pk_mul_f32 v[56:57], v[6:7], v[74:75]
	v_pk_mul_f32 v[54:55], v[4:5], v[72:73]
	v_add_f32_dpp v52, v52, v52 quad_perm:[2,3,0,1] row_mask:0xf bank_mask:0xf bound_ctrl:1
	v_pk_fma_f32 v[56:57], v[86:87], v[92:93], v[56:57] op_sel_hi:[1,0,1]
	v_pk_fma_f32 v[54:55], v[84:85], v[92:93], v[54:55] op_sel_hi:[1,0,1]
	v_add_f32_dpp v52, v52, v52 row_half_mirror row_mask:0xf bank_mask:0xf bound_ctrl:1
	v_pk_mul_f32 v[26:27], v[6:7], v[42:43]
	v_add_f32_dpp v34, v25, v25 row_ror:8 row_mask:0xf bank_mask:0x3
	v_add_f32_dpp v52, v52, v52 row_mirror row_mask:0xf bank_mask:0xf bound_ctrl:1
	v_pk_mul_f32 v[114:115], v[56:57], v[78:79]
	v_pk_mul_f32 v[116:117], v[106:107], v[78:79]
	v_pk_fma_f32 v[114:115], v[54:55], v[76:77], v[114:115]
	v_pk_fma_f32 v[116:117], v[104:105], v[76:77], v[116:117]
	v_pk_fma_f32 v[26:27], v[4:5], v[40:41], v[26:27]
	v_add_f32_e32 v118, v114, v115
	v_add_f32_e32 v119, v116, v117
	ds_read_b128 v[68:71], v9 offset:2944
	ds_read_b128 v[64:67], v9 offset:1344
	ds_read_b128 v[28:31], v9 offset:2112
	ds_read_b32 v32, v10 offset:2624
	ds_read_b128 v[48:51], v9 offset:1856
	ds_read_b128 v[36:39], v9 offset:1024
	v_add_f32_e32 v25, v26, v27
	global_store_dword v2, v33, s[4:5]
	s_waitcnt lgkmcnt(11)
	v_fma_f32 v112, v119, v52, v118
	v_pk_fma_f32 v[6:7], v[106:107], v[52:53], v[56:57] op_sel_hi:[1,0,1]
	v_pk_fma_f32 v[4:5], v[104:105], v[52:53], v[54:55] op_sel_hi:[1,0,1]
	v_add_f32_dpp v112, v112, v112 quad_perm:[1,0,3,2] row_mask:0xf bank_mask:0xf bound_ctrl:1
	v_pk_mul_f32 v[56:57], v[6:7], v[82:83]
	v_pk_mul_f32 v[54:55], v[4:5], v[80:81]
	v_add_f32_dpp v112, v112, v112 quad_perm:[2,3,0,1] row_mask:0xf bank_mask:0xf bound_ctrl:1
	v_pk_fma_f32 v[56:57], v[90:91], v[94:95], v[56:57] op_sel_hi:[1,0,1]
	v_pk_fma_f32 v[54:55], v[88:89], v[94:95], v[54:55] op_sel_hi:[1,0,1]
	v_add_f32_dpp v112, v112, v112 row_half_mirror row_mask:0xf bank_mask:0xf bound_ctrl:1
	v_pk_mul_f32 v[26:27], v[6:7], v[98:99]
	v_add_f32_dpp v34, v25, v25 row_ror:8 row_mask:0xf bank_mask:0xc
	v_add_f32_dpp v112, v112, v112 row_mirror row_mask:0xf bank_mask:0xf bound_ctrl:1
	v_pk_mul_f32 v[114:115], v[56:57], v[14:15]
	v_pk_mul_f32 v[116:117], v[110:111], v[14:15]
	v_pk_fma_f32 v[114:115], v[54:55], v[12:13], v[114:115]
	v_pk_fma_f32 v[116:117], v[108:109], v[12:13], v[116:117]
	v_pk_fma_f32 v[26:27], v[4:5], v[96:97], v[26:27]
	v_add_f32_e32 v118, v114, v115
	v_add_f32_e32 v119, v116, v117
	ds_read_b128 v[76:79], v9 offset:4288
	ds_read_b128 v[72:75], v9 offset:2688
	ds_read_b128 v[84:87], v9 offset:3456
	ds_read_b32 v92, v10 offset:3968
	ds_read_b128 v[104:107], v9 offset:3200
	ds_read_b128 v[40:43], v9 offset:2368
	v_add_f32_e32 v25, v26, v27
	v_add_f32_dpp v11, v34, v34 row_half_mirror row_mask:0xf bank_mask:0x5
	s_nop 0
	v_add_f32_dpp v34, v25, v25 row_ror:8 row_mask:0xf bank_mask:0x3
	v_pk_fma_f32 v[6:7], v[110:111], v[112:113], v[56:57] op_sel_hi:[1,0,1]
	v_pk_fma_f32 v[4:5], v[108:109], v[112:113], v[54:55] op_sel_hi:[1,0,1]
	v_cndmask_b32_e64 v255, v35, v58, s[40:41]
	v_pk_mul_f32 v[26:27], v[6:7], v[102:103]
	v_cndmask_b32_e64 v8, v58, v35, s[40:41]
	v_pk_fma_f32 v[26:27], v[4:5], v[100:101], v[26:27]
	s_nop 0
	v_add_f32_e32 v25, v26, v27
	v_add_f32_dpp v253, v8, v255 quad_perm:[2,3,0,1] row_mask:0xf bank_mask:0xf bound_ctrl:1
	s_nop 0
	v_add_f32_dpp v34, v25, v25 row_ror:8 row_mask:0xf bank_mask:0xc
	s_nop 1
	v_add_f32_dpp v11, v34, v34 row_half_mirror row_mask:0xf bank_mask:0xa
	s_nop 1
	v_cndmask_b32_e64 v255, v0, v11, s[40:41]
	v_cndmask_b32_e64 v8, v11, v0, s[40:41]
	s_nop 1
	v_add_f32_dpp v254, v8, v255 quad_perm:[2,3,0,1] row_mask:0xf bank_mask:0xf bound_ctrl:1
	v_cndmask_b32_e64 v255, v253, v254, s[42:43]
	v_cndmask_b32_e64 v8, v254, v253, s[42:43]
	s_add_i32 s3, s3, 1
	s_nop 0
	v_add_f32_dpp v33, v8, v255 quad_perm:[1,0,3,2] row_mask:0xf bank_mask:0xf bound_ctrl:1
	global_store_dword v3, v33, s[4:5]
	s_add_u32 s4, s4, 0x20000
	s_addc_u32 s5, s5, 0
	s_cmp_lg_u32 s3, 0x100
	s_cbranch_scc1 .Lscan_top
	s_waitcnt lgkmcnt(0)
	s_setprio 0
	v_readlane_b32 s60, v250, 1
	v_readlane_b32 s61, v250, 2
	s_mov_b64 s[62:63], s[90:91]
